# v36 + non-temporal hints on the P3 cross-chunk scan loads and stores (read-once / write-once 8-byte streams)
# baseline (speedup 1.0000x reference)
; DI unsigned pk2(float lo, float hi) { f32x2 v = {lo, hi}; return __builtin_bit_cast(unsigned, __builtin_convertvector(v, bf16x2v)); }
; DI float bflo(unsigned u) { return __uint_as_float(u << 16); }
; DI float bfhi(unsigned u) { return __uint_as_float(u & 0xffff0000u); }
; DI void ret_scan(const bf16_t* KV, bf16_t* SP, float* o_state, int gt, int nthreads) {
;     ...
;         for (int n0 = 0; n0 < 64; n0 += 32) {
;             u32x2 q[32];
; #pragma unroll
;             for (int u = 0; u < 32; ++u) q[u] = *(const u32x2*)(KV + (size_t)(n0 + u) * 262144 + base);
; #pragma unroll
;             for (int u = 0; u < 32; ++u) { u32x2 o; o.x = pk2(s[0], s[1]); o.y = pk2(s[2], s[3]); *(u32x2*)(SP + (size_t)(n0 + u) * 262144 + base) = o;
;                 const f32x4 kv = {bflo(q[u].x), bfhi(q[u].x), bflo(q[u].y), bfhi(q[u].y)}; s = s * Dc + kv * c1; }
.LBB0_308:
	v_cndmask_b32_e64 v20, 0, 1, s[18:19]
	s_lshl_b64 s[6:7], s[16:17], 1
	v_cmp_ne_u32_e32 vcc, 1, v20
	v_lshl_add_u64 v[20:21], v[8:9], 0, s[6:7]
	global_load_dwordx2 v[82:83], v[20:21], off nt
	s_or_b32 s0, s16, 0x40000
	s_mov_b32 s1, s17
	s_lshl_b64 s[8:9], s[0:1], 1
	v_lshl_add_u64 v[20:21], v[8:9], 0, s[8:9]
	s_or_b32 s0, s16, 0x80000
	global_load_dwordx2 v[80:81], v[20:21], off nt
	s_lshl_b64 s[4:5], s[0:1], 1
	v_lshl_add_u64 v[20:21], v[8:9], 0, s[4:5]
	s_or_b32 s0, s16, 0xc0000
	global_load_dwordx2 v[78:79], v[20:21], off nt
	s_lshl_b64 s[12:13], s[0:1], 1
	v_lshl_add_u64 v[20:21], v[8:9], 0, s[12:13]
	s_or_b32 s0, s16, 0x100000
	global_load_dwordx2 v[76:77], v[20:21], off nt
	s_lshl_b64 s[0:1], s[0:1], 1
	v_lshl_add_u64 v[20:21], v[8:9], 0, s[0:1]
	s_or_b32 s18, s16, 0x140000
	s_mov_b32 s19, s17
	global_load_dwordx2 v[74:75], v[20:21], off nt
	s_lshl_b64 s[96:97], s[18:19], 1
	v_lshl_add_u64 v[20:21], v[8:9], 0, s[96:97]
	s_or_b32 s18, s16, 0x180000
	global_load_dwordx2 v[72:73], v[20:21], off nt
	s_lshl_b64 s[94:95], s[18:19], 1
	v_lshl_add_u64 v[20:21], v[8:9], 0, s[94:95]
	s_or_b32 s18, s16, 0x1c0000
	global_load_dwordx2 v[70:71], v[20:21], off nt
	s_lshl_b64 s[92:93], s[18:19], 1
	v_lshl_add_u64 v[20:21], v[8:9], 0, s[92:93]
	s_or_b32 s18, s16, 0x200000
	global_load_dwordx2 v[68:69], v[20:21], off nt
	s_lshl_b64 s[90:91], s[18:19], 1
	v_lshl_add_u64 v[20:21], v[8:9], 0, s[90:91]
	s_or_b32 s18, s16, 0x240000
	global_load_dwordx2 v[66:67], v[20:21], off nt
	s_lshl_b64 s[88:89], s[18:19], 1
	v_lshl_add_u64 v[20:21], v[8:9], 0, s[88:89]
	s_or_b32 s18, s16, 0x280000
	global_load_dwordx2 v[64:65], v[20:21], off nt
	s_lshl_b64 s[86:87], s[18:19], 1
	v_lshl_add_u64 v[20:21], v[8:9], 0, s[86:87]
	s_or_b32 s18, s16, 0x2c0000
	global_load_dwordx2 v[62:63], v[20:21], off nt
	s_lshl_b64 s[84:85], s[18:19], 1
	v_lshl_add_u64 v[20:21], v[8:9], 0, s[84:85]
	s_or_b32 s18, s16, 0x300000
	global_load_dwordx2 v[60:61], v[20:21], off nt
	s_lshl_b64 s[82:83], s[18:19], 1
	v_lshl_add_u64 v[20:21], v[8:9], 0, s[82:83]
	s_or_b32 s18, s16, 0x340000
	global_load_dwordx2 v[58:59], v[20:21], off nt
	s_lshl_b64 s[80:81], s[18:19], 1
	v_lshl_add_u64 v[20:21], v[8:9], 0, s[80:81]
	s_or_b32 s18, s16, 0x380000
	global_load_dwordx2 v[56:57], v[20:21], off nt
	s_lshl_b64 s[78:79], s[18:19], 1
	v_lshl_add_u64 v[20:21], v[8:9], 0, s[78:79]
	s_or_b32 s18, s16, 0x3c0000
	global_load_dwordx2 v[54:55], v[20:21], off nt
	s_lshl_b64 s[76:77], s[18:19], 1
	v_lshl_add_u64 v[20:21], v[8:9], 0, s[76:77]
	s_or_b32 s18, s16, 0x400000
	global_load_dwordx2 v[52:53], v[20:21], off nt
	s_lshl_b64 s[74:75], s[18:19], 1
	v_lshl_add_u64 v[20:21], v[8:9], 0, s[74:75]
	s_or_b32 s18, s16, 0x440000
	global_load_dwordx2 v[50:51], v[20:21], off nt
	s_lshl_b64 s[72:73], s[18:19], 1
	v_lshl_add_u64 v[20:21], v[8:9], 0, s[72:73]
	s_or_b32 s18, s16, 0x480000
	global_load_dwordx2 v[48:49], v[20:21], off nt
	s_lshl_b64 s[70:71], s[18:19], 1
	v_lshl_add_u64 v[20:21], v[8:9], 0, s[70:71]
	s_or_b32 s18, s16, 0x4c0000
	global_load_dwordx2 v[46:47], v[20:21], off nt
	s_lshl_b64 s[68:69], s[18:19], 1
	v_lshl_add_u64 v[20:21], v[8:9], 0, s[68:69]
	s_or_b32 s18, s16, 0x500000
	global_load_dwordx2 v[44:45], v[20:21], off nt
	s_lshl_b64 s[42:43], s[18:19], 1
	v_lshl_add_u64 v[20:21], v[8:9], 0, s[42:43]
	s_or_b32 s18, s16, 0x540000
	global_load_dwordx2 v[42:43], v[20:21], off nt
	s_lshl_b64 s[40:41], s[18:19], 1
	v_lshl_add_u64 v[20:21], v[8:9], 0, s[40:41]
	s_or_b32 s18, s16, 0x580000
	global_load_dwordx2 v[40:41], v[20:21], off nt
	s_lshl_b64 s[38:39], s[18:19], 1
	v_lshl_add_u64 v[20:21], v[8:9], 0, s[38:39]
	s_or_b32 s18, s16, 0x5c0000
	global_load_dwordx2 v[38:39], v[20:21], off nt
	s_lshl_b64 s[36:37], s[18:19], 1
	v_lshl_add_u64 v[20:21], v[8:9], 0, s[36:37]
	s_or_b32 s18, s16, 0x600000
	global_load_dwordx2 v[36:37], v[20:21], off nt
	s_lshl_b64 s[34:35], s[18:19], 1
	v_lshl_add_u64 v[20:21], v[8:9], 0, s[34:35]
	s_or_b32 s18, s16, 0x640000
	global_load_dwordx2 v[34:35], v[20:21], off nt
	s_lshl_b64 s[30:31], s[18:19], 1
	v_lshl_add_u64 v[20:21], v[8:9], 0, s[30:31]
	s_or_b32 s18, s16, 0x680000
	global_load_dwordx2 v[32:33], v[20:21], off nt
	s_lshl_b64 s[28:29], s[18:19], 1
	v_lshl_add_u64 v[20:21], v[8:9], 0, s[28:29]
	s_or_b32 s18, s16, 0x6c0000
	global_load_dwordx2 v[30:31], v[20:21], off nt
	v_cvt_pk_bf16_f32 v92, v18, v19
	v_cvt_pk_bf16_f32 v93, v16, v17
	v_lshl_add_u64 v[94:95], v[10:11], 0, s[6:7]
	s_lshl_b64 s[26:27], s[18:19], 1
	global_store_dwordx2 v[94:95], v[92:93], off nt
	s_waitcnt vmcnt(0)
; DI unsigned pk2(float lo, float hi) { f32x2 v = {lo, hi}; return __builtin_bit_cast(unsigned, __builtin_convertvector(v, bf16x2v)); }
; DI float bflo(unsigned u) { return __uint_as_float(u << 16); }
; DI float bfhi(unsigned u) { return __uint_as_float(u & 0xffff0000u); }
; DI void ret_scan(const bf16_t* KV, bf16_t* SP, float* o_state, int gt, int nthreads) {
;     ...
;             for (int u = 0; u < 32; ++u) q[u] = *(const u32x2*)(KV + (size_t)(n0 + u) * 262144 + base);
; #pragma unroll
;             for (int u = 0; u < 32; ++u) { u32x2 o; o.x = pk2(s[0], s[1]); o.y = pk2(s[2], s[3]); *(u32x2*)(SP + (size_t)(n0 + u) * 262144 + base) = o;
;                 const f32x4 kv = {bflo(q[u].x), bfhi(q[u].x), bflo(q[u].y), bfhi(q[u].y)}; s = s * Dc + kv * c1; }
	v_lshlrev_b32_e32 v92, 16, v82
	v_and_b32_e32 v93, 0xffff0000, v82
	v_lshlrev_b32_e32 v82, 16, v83
	v_and_b32_e32 v83, 0xffff0000, v83
	v_lshl_add_u64 v[20:21], v[8:9], 0, s[26:27]
	v_pk_mul_f32 v[92:93], v[6:7], v[92:93]
	v_pk_mul_f32 v[82:83], v[14:15], v[82:83]
	s_or_b32 s18, s16, 0x700000
	global_load_dwordx2 v[28:29], v[20:21], off nt
	v_pk_fma_f32 v[16:17], v[12:13], v[16:17], v[82:83]
	v_pk_fma_f32 v[18:19], v[4:5], v[18:19], v[92:93]
	s_lshl_b64 s[24:25], s[18:19], 1
	v_cvt_pk_bf16_f32 v82, v18, v19
	v_cvt_pk_bf16_f32 v83, v16, v17
	v_lshl_add_u64 v[92:93], v[10:11], 0, s[8:9]
	v_lshl_add_u64 v[20:21], v[8:9], 0, s[24:25]
	global_store_dwordx2 v[92:93], v[82:83], off nt
	v_lshlrev_b32_e32 v82, 16, v80
	v_and_b32_e32 v83, 0xffff0000, v80
	v_lshlrev_b32_e32 v80, 16, v81
	v_and_b32_e32 v81, 0xffff0000, v81
	v_pk_mul_f32 v[18:19], v[4:5], v[18:19]
	v_pk_mul_f32 v[16:17], v[12:13], v[16:17]
	s_or_b32 s18, s16, 0x740000
	global_load_dwordx2 v[26:27], v[20:21], off nt
	v_pk_fma_f32 v[16:17], v[14:15], v[80:81], v[16:17]
	v_pk_fma_f32 v[18:19], v[6:7], v[82:83], v[18:19]
	s_lshl_b64 s[22:23], s[18:19], 1
	v_cvt_pk_bf16_f32 v80, v18, v19
	v_cvt_pk_bf16_f32 v81, v16, v17
	v_lshl_add_u64 v[82:83], v[10:11], 0, s[4:5]
	v_lshl_add_u64 v[20:21], v[8:9], 0, s[22:23]
	global_store_dwordx2 v[82:83], v[80:81], off nt
	v_lshlrev_b32_e32 v80, 16, v78
	v_and_b32_e32 v81, 0xffff0000, v78
	v_lshlrev_b32_e32 v78, 16, v79
	v_and_b32_e32 v79, 0xffff0000, v79
	v_pk_mul_f32 v[18:19], v[4:5], v[18:19]
	v_pk_mul_f32 v[16:17], v[12:13], v[16:17]
	s_or_b32 s18, s16, 0x780000
	global_load_dwordx2 v[24:25], v[20:21], off nt
	v_pk_fma_f32 v[16:17], v[14:15], v[78:79], v[16:17]
	v_pk_fma_f32 v[18:19], v[6:7], v[80:81], v[18:19]
	s_lshl_b64 s[20:21], s[18:19], 1
	v_cvt_pk_bf16_f32 v78, v18, v19
	v_cvt_pk_bf16_f32 v79, v16, v17
	v_lshl_add_u64 v[80:81], v[10:11], 0, s[12:13]
	v_lshl_add_u64 v[20:21], v[8:9], 0, s[20:21]
	global_store_dwordx2 v[80:81], v[78:79], off nt
	v_lshlrev_b32_e32 v78, 16, v76
	v_and_b32_e32 v79, 0xffff0000, v76
	v_lshlrev_b32_e32 v76, 16, v77
	v_and_b32_e32 v77, 0xffff0000, v77
	v_pk_mul_f32 v[18:19], v[4:5], v[18:19]
	v_pk_mul_f32 v[16:17], v[12:13], v[16:17]
	s_or_b32 s16, s16, 0x7c0000
	global_load_dwordx2 v[22:23], v[20:21], off nt
	v_pk_fma_f32 v[16:17], v[14:15], v[76:77], v[16:17]
	v_pk_fma_f32 v[18:19], v[6:7], v[78:79], v[18:19]
	s_lshl_b64 s[18:19], s[16:17], 1
	v_cvt_pk_bf16_f32 v76, v18, v19
	v_cvt_pk_bf16_f32 v77, v16, v17
	v_lshl_add_u64 v[78:79], v[10:11], 0, s[0:1]
	v_lshl_add_u64 v[20:21], v[8:9], 0, s[18:19]
	global_store_dwordx2 v[78:79], v[76:77], off nt
	v_lshlrev_b32_e32 v76, 16, v74
	v_and_b32_e32 v77, 0xffff0000, v74
	v_lshlrev_b32_e32 v74, 16, v75
	v_and_b32_e32 v75, 0xffff0000, v75
	v_pk_mul_f32 v[18:19], v[4:5], v[18:19]
	v_pk_mul_f32 v[16:17], v[12:13], v[16:17]
	global_load_dwordx2 v[20:21], v[20:21], off nt
	v_pk_fma_f32 v[16:17], v[14:15], v[74:75], v[16:17]
	v_pk_fma_f32 v[18:19], v[6:7], v[76:77], v[18:19]
	v_cvt_pk_bf16_f32 v75, v16, v17
	v_cvt_pk_bf16_f32 v74, v18, v19
	v_lshl_add_u64 v[76:77], v[10:11], 0, s[96:97]
	global_store_dwordx2 v[76:77], v[74:75], off nt
	v_lshlrev_b32_e32 v74, 16, v72
	v_and_b32_e32 v75, 0xffff0000, v72
	v_lshlrev_b32_e32 v72, 16, v73
	v_and_b32_e32 v73, 0xffff0000, v73
	v_pk_mul_f32 v[18:19], v[4:5], v[18:19]
	v_pk_mul_f32 v[16:17], v[12:13], v[16:17]
	v_pk_fma_f32 v[18:19], v[6:7], v[74:75], v[18:19]
	v_pk_fma_f32 v[16:17], v[14:15], v[72:73], v[16:17]
	v_cvt_pk_bf16_f32 v72, v18, v19
	v_cvt_pk_bf16_f32 v73, v16, v17
	v_lshl_add_u64 v[74:75], v[10:11], 0, s[94:95]
	global_store_dwordx2 v[74:75], v[72:73], off nt
	v_lshlrev_b32_e32 v72, 16, v70
	v_and_b32_e32 v73, 0xffff0000, v70
	v_lshlrev_b32_e32 v70, 16, v71
	v_and_b32_e32 v71, 0xffff0000, v71
	v_pk_mul_f32 v[18:19], v[4:5], v[18:19]
	v_pk_mul_f32 v[16:17], v[12:13], v[16:17]
	v_pk_fma_f32 v[18:19], v[6:7], v[72:73], v[18:19]
	v_pk_fma_f32 v[16:17], v[14:15], v[70:71], v[16:17]
	v_cvt_pk_bf16_f32 v70, v18, v19
	v_cvt_pk_bf16_f32 v71, v16, v17
	v_lshl_add_u64 v[72:73], v[10:11], 0, s[92:93]
	global_store_dwordx2 v[72:73], v[70:71], off nt
	v_lshlrev_b32_e32 v70, 16, v68
	v_and_b32_e32 v71, 0xffff0000, v68
	v_lshlrev_b32_e32 v68, 16, v69
	v_and_b32_e32 v69, 0xffff0000, v69
	v_pk_mul_f32 v[18:19], v[4:5], v[18:19]
	v_pk_mul_f32 v[16:17], v[12:13], v[16:17]
	v_pk_fma_f32 v[18:19], v[6:7], v[70:71], v[18:19]
	v_pk_fma_f32 v[16:17], v[14:15], v[68:69], v[16:17]
	v_cvt_pk_bf16_f32 v68, v18, v19
	v_cvt_pk_bf16_f32 v69, v16, v17
	v_lshl_add_u64 v[70:71], v[10:11], 0, s[90:91]
	global_store_dwordx2 v[70:71], v[68:69], off nt
	v_lshlrev_b32_e32 v68, 16, v66
	v_and_b32_e32 v69, 0xffff0000, v66
	v_lshlrev_b32_e32 v66, 16, v67
	v_and_b32_e32 v67, 0xffff0000, v67
	v_pk_mul_f32 v[18:19], v[4:5], v[18:19]
	v_pk_mul_f32 v[16:17], v[12:13], v[16:17]
	v_pk_fma_f32 v[18:19], v[6:7], v[68:69], v[18:19]
	v_pk_fma_f32 v[16:17], v[14:15], v[66:67], v[16:17]
	v_cvt_pk_bf16_f32 v66, v18, v19
	v_cvt_pk_bf16_f32 v67, v16, v17
	v_lshl_add_u64 v[68:69], v[10:11], 0, s[88:89]
	global_store_dwordx2 v[68:69], v[66:67], off nt
	v_lshlrev_b32_e32 v66, 16, v64
	v_and_b32_e32 v67, 0xffff0000, v64
	v_lshlrev_b32_e32 v64, 16, v65
	v_and_b32_e32 v65, 0xffff0000, v65
	v_pk_mul_f32 v[18:19], v[4:5], v[18:19]
	v_pk_mul_f32 v[16:17], v[12:13], v[16:17]
	v_pk_fma_f32 v[18:19], v[6:7], v[66:67], v[18:19]
	v_pk_fma_f32 v[16:17], v[14:15], v[64:65], v[16:17]
	v_cvt_pk_bf16_f32 v64, v18, v19
	v_cvt_pk_bf16_f32 v65, v16, v17
	v_lshl_add_u64 v[66:67], v[10:11], 0, s[86:87]
	global_store_dwordx2 v[66:67], v[64:65], off nt
	v_lshlrev_b32_e32 v64, 16, v62
	v_and_b32_e32 v65, 0xffff0000, v62
; DI unsigned pk2(float lo, float hi) { f32x2 v = {lo, hi}; return __builtin_bit_cast(unsigned, __builtin_convertvector(v, bf16x2v)); }
; DI float bflo(unsigned u) { return __uint_as_float(u << 16); }
; DI float bfhi(unsigned u) { return __uint_as_float(u & 0xffff0000u); }
; DI void ret_scan(const bf16_t* KV, bf16_t* SP, float* o_state, int gt, int nthreads) {
;     ...
;             for (int u = 0; u < 32; ++u) q[u] = *(const u32x2*)(KV + (size_t)(n0 + u) * 262144 + base);
; #pragma unroll
;             for (int u = 0; u < 32; ++u) { u32x2 o; o.x = pk2(s[0], s[1]); o.y = pk2(s[2], s[3]); *(u32x2*)(SP + (size_t)(n0 + u) * 262144 + base) = o;
;                 const f32x4 kv = {bflo(q[u].x), bfhi(q[u].x), bflo(q[u].y), bfhi(q[u].y)}; s = s * Dc + kv * c1; }
	v_lshlrev_b32_e32 v62, 16, v63
	v_and_b32_e32 v63, 0xffff0000, v63
	v_pk_mul_f32 v[18:19], v[4:5], v[18:19]
	v_pk_mul_f32 v[16:17], v[12:13], v[16:17]
	v_pk_fma_f32 v[18:19], v[6:7], v[64:65], v[18:19]
	v_pk_fma_f32 v[16:17], v[14:15], v[62:63], v[16:17]
	v_cvt_pk_bf16_f32 v62, v18, v19
	v_cvt_pk_bf16_f32 v63, v16, v17
	v_lshl_add_u64 v[64:65], v[10:11], 0, s[84:85]
	global_store_dwordx2 v[64:65], v[62:63], off nt
	v_lshlrev_b32_e32 v62, 16, v60
	v_and_b32_e32 v63, 0xffff0000, v60
	v_lshlrev_b32_e32 v60, 16, v61
	v_and_b32_e32 v61, 0xffff0000, v61
	v_pk_mul_f32 v[18:19], v[4:5], v[18:19]
	v_pk_mul_f32 v[16:17], v[12:13], v[16:17]
	v_pk_fma_f32 v[18:19], v[6:7], v[62:63], v[18:19]
	v_pk_fma_f32 v[16:17], v[14:15], v[60:61], v[16:17]
	v_cvt_pk_bf16_f32 v60, v18, v19
	v_cvt_pk_bf16_f32 v61, v16, v17
	v_lshl_add_u64 v[62:63], v[10:11], 0, s[82:83]
	global_store_dwordx2 v[62:63], v[60:61], off nt
	v_lshlrev_b32_e32 v60, 16, v58
	v_and_b32_e32 v61, 0xffff0000, v58
	v_lshlrev_b32_e32 v58, 16, v59
	v_and_b32_e32 v59, 0xffff0000, v59
	v_pk_mul_f32 v[18:19], v[4:5], v[18:19]
	v_pk_mul_f32 v[16:17], v[12:13], v[16:17]
	v_pk_fma_f32 v[18:19], v[6:7], v[60:61], v[18:19]
	v_pk_fma_f32 v[16:17], v[14:15], v[58:59], v[16:17]
	v_cvt_pk_bf16_f32 v58, v18, v19
	v_cvt_pk_bf16_f32 v59, v16, v17
	v_lshl_add_u64 v[60:61], v[10:11], 0, s[80:81]
	global_store_dwordx2 v[60:61], v[58:59], off nt
	v_lshlrev_b32_e32 v58, 16, v56
	v_and_b32_e32 v59, 0xffff0000, v56
	v_lshlrev_b32_e32 v56, 16, v57
	v_and_b32_e32 v57, 0xffff0000, v57
	v_pk_mul_f32 v[18:19], v[4:5], v[18:19]
	v_pk_mul_f32 v[16:17], v[12:13], v[16:17]
	v_pk_fma_f32 v[18:19], v[6:7], v[58:59], v[18:19]
	v_pk_fma_f32 v[16:17], v[14:15], v[56:57], v[16:17]
	v_cvt_pk_bf16_f32 v56, v18, v19
	v_cvt_pk_bf16_f32 v57, v16, v17
	v_lshl_add_u64 v[58:59], v[10:11], 0, s[78:79]
	global_store_dwordx2 v[58:59], v[56:57], off nt
	v_lshlrev_b32_e32 v56, 16, v54
	v_and_b32_e32 v57, 0xffff0000, v54
	v_lshlrev_b32_e32 v54, 16, v55
	v_and_b32_e32 v55, 0xffff0000, v55
	v_pk_mul_f32 v[18:19], v[4:5], v[18:19]
	v_pk_mul_f32 v[16:17], v[12:13], v[16:17]
	v_pk_fma_f32 v[18:19], v[6:7], v[56:57], v[18:19]
	v_pk_fma_f32 v[16:17], v[14:15], v[54:55], v[16:17]
	v_cvt_pk_bf16_f32 v54, v18, v19
	v_cvt_pk_bf16_f32 v55, v16, v17
	v_lshl_add_u64 v[56:57], v[10:11], 0, s[76:77]
	global_store_dwordx2 v[56:57], v[54:55], off nt
	v_lshlrev_b32_e32 v54, 16, v52
	v_and_b32_e32 v55, 0xffff0000, v52
	v_lshlrev_b32_e32 v52, 16, v53
	v_and_b32_e32 v53, 0xffff0000, v53
	v_pk_mul_f32 v[18:19], v[4:5], v[18:19]
	v_pk_mul_f32 v[16:17], v[12:13], v[16:17]
	v_pk_fma_f32 v[18:19], v[6:7], v[54:55], v[18:19]
	v_pk_fma_f32 v[16:17], v[14:15], v[52:53], v[16:17]
	v_cvt_pk_bf16_f32 v52, v18, v19
	v_cvt_pk_bf16_f32 v53, v16, v17
	v_lshl_add_u64 v[54:55], v[10:11], 0, s[74:75]
	global_store_dwordx2 v[54:55], v[52:53], off nt
	v_lshlrev_b32_e32 v52, 16, v50
	v_and_b32_e32 v53, 0xffff0000, v50
	v_lshlrev_b32_e32 v50, 16, v51
	v_and_b32_e32 v51, 0xffff0000, v51
	v_pk_mul_f32 v[18:19], v[4:5], v[18:19]
	v_pk_mul_f32 v[16:17], v[12:13], v[16:17]
	v_pk_fma_f32 v[18:19], v[6:7], v[52:53], v[18:19]
	v_pk_fma_f32 v[16:17], v[14:15], v[50:51], v[16:17]
	v_cvt_pk_bf16_f32 v50, v18, v19
	v_cvt_pk_bf16_f32 v51, v16, v17
	v_lshl_add_u64 v[52:53], v[10:11], 0, s[72:73]
	global_store_dwordx2 v[52:53], v[50:51], off nt
	v_lshlrev_b32_e32 v50, 16, v48
	v_and_b32_e32 v51, 0xffff0000, v48
	v_lshlrev_b32_e32 v48, 16, v49
	v_and_b32_e32 v49, 0xffff0000, v49
	v_pk_mul_f32 v[18:19], v[4:5], v[18:19]
	v_pk_mul_f32 v[16:17], v[12:13], v[16:17]
	v_pk_fma_f32 v[18:19], v[6:7], v[50:51], v[18:19]
	v_pk_fma_f32 v[16:17], v[14:15], v[48:49], v[16:17]
	v_cvt_pk_bf16_f32 v48, v18, v19
	v_cvt_pk_bf16_f32 v49, v16, v17
	v_lshl_add_u64 v[50:51], v[10:11], 0, s[70:71]
	global_store_dwordx2 v[50:51], v[48:49], off nt
	v_lshlrev_b32_e32 v48, 16, v46
	v_and_b32_e32 v49, 0xffff0000, v46
	v_lshlrev_b32_e32 v46, 16, v47
	v_and_b32_e32 v47, 0xffff0000, v47
	v_pk_mul_f32 v[18:19], v[4:5], v[18:19]
	v_pk_mul_f32 v[16:17], v[12:13], v[16:17]
	v_pk_fma_f32 v[18:19], v[6:7], v[48:49], v[18:19]
	v_pk_fma_f32 v[16:17], v[14:15], v[46:47], v[16:17]
	v_cvt_pk_bf16_f32 v46, v18, v19
	v_cvt_pk_bf16_f32 v47, v16, v17
	v_lshl_add_u64 v[48:49], v[10:11], 0, s[68:69]
	global_store_dwordx2 v[48:49], v[46:47], off nt
	v_lshlrev_b32_e32 v46, 16, v44
	v_and_b32_e32 v47, 0xffff0000, v44
	v_lshlrev_b32_e32 v44, 16, v45
	v_and_b32_e32 v45, 0xffff0000, v45
	v_pk_mul_f32 v[18:19], v[4:5], v[18:19]
	v_pk_mul_f32 v[16:17], v[12:13], v[16:17]
	v_pk_fma_f32 v[18:19], v[6:7], v[46:47], v[18:19]
	v_pk_fma_f32 v[16:17], v[14:15], v[44:45], v[16:17]
	v_cvt_pk_bf16_f32 v44, v18, v19
	v_cvt_pk_bf16_f32 v45, v16, v17
	v_lshl_add_u64 v[46:47], v[10:11], 0, s[42:43]
	global_store_dwordx2 v[46:47], v[44:45], off nt
	v_lshlrev_b32_e32 v44, 16, v42
	v_and_b32_e32 v45, 0xffff0000, v42
	v_lshlrev_b32_e32 v42, 16, v43
	v_and_b32_e32 v43, 0xffff0000, v43
	v_pk_mul_f32 v[18:19], v[4:5], v[18:19]
	v_pk_mul_f32 v[16:17], v[12:13], v[16:17]
	v_pk_fma_f32 v[18:19], v[6:7], v[44:45], v[18:19]
	v_pk_fma_f32 v[16:17], v[14:15], v[42:43], v[16:17]
	v_cvt_pk_bf16_f32 v42, v18, v19
	v_cvt_pk_bf16_f32 v43, v16, v17
	v_lshl_add_u64 v[44:45], v[10:11], 0, s[40:41]
	global_store_dwordx2 v[44:45], v[42:43], off nt
	v_lshlrev_b32_e32 v42, 16, v40
	v_and_b32_e32 v43, 0xffff0000, v40
	v_lshlrev_b32_e32 v40, 16, v41
	v_and_b32_e32 v41, 0xffff0000, v41
	v_pk_mul_f32 v[18:19], v[4:5], v[18:19]
	v_pk_mul_f32 v[16:17], v[12:13], v[16:17]
	v_pk_fma_f32 v[18:19], v[6:7], v[42:43], v[18:19]
	v_pk_fma_f32 v[16:17], v[14:15], v[40:41], v[16:17]
	v_cvt_pk_bf16_f32 v40, v18, v19
; DI unsigned pk2(float lo, float hi) { f32x2 v = {lo, hi}; return __builtin_bit_cast(unsigned, __builtin_convertvector(v, bf16x2v)); }
; DI float bflo(unsigned u) { return __uint_as_float(u << 16); }
; DI float bfhi(unsigned u) { return __uint_as_float(u & 0xffff0000u); }
; DI void ret_scan(const bf16_t* KV, bf16_t* SP, float* o_state, int gt, int nthreads) {
;     ...
;             for (int u = 0; u < 32; ++u) q[u] = *(const u32x2*)(KV + (size_t)(n0 + u) * 262144 + base);
; #pragma unroll
;             for (int u = 0; u < 32; ++u) { u32x2 o; o.x = pk2(s[0], s[1]); o.y = pk2(s[2], s[3]); *(u32x2*)(SP + (size_t)(n0 + u) * 262144 + base) = o;
;                 const f32x4 kv = {bflo(q[u].x), bfhi(q[u].x), bflo(q[u].y), bfhi(q[u].y)}; s = s * Dc + kv * c1; }
;         }
; #pragma unroll
;         for (int j = 0; j < 4; ++j) o_state[((size_t)(h * 256 + dk4 + j)) * 256 + dv] = s[j];
	v_cvt_pk_bf16_f32 v41, v16, v17
	v_lshl_add_u64 v[42:43], v[10:11], 0, s[38:39]
	global_store_dwordx2 v[42:43], v[40:41], off nt
	v_lshlrev_b32_e32 v40, 16, v38
	v_and_b32_e32 v41, 0xffff0000, v38
	v_lshlrev_b32_e32 v38, 16, v39
	v_and_b32_e32 v39, 0xffff0000, v39
	v_pk_mul_f32 v[18:19], v[4:5], v[18:19]
	v_pk_mul_f32 v[16:17], v[12:13], v[16:17]
	v_pk_fma_f32 v[18:19], v[6:7], v[40:41], v[18:19]
	v_pk_fma_f32 v[16:17], v[14:15], v[38:39], v[16:17]
	v_cvt_pk_bf16_f32 v38, v18, v19
	v_cvt_pk_bf16_f32 v39, v16, v17
	v_lshl_add_u64 v[40:41], v[10:11], 0, s[36:37]
	global_store_dwordx2 v[40:41], v[38:39], off nt
	v_lshlrev_b32_e32 v38, 16, v36
	v_and_b32_e32 v39, 0xffff0000, v36
	v_lshlrev_b32_e32 v36, 16, v37
	v_and_b32_e32 v37, 0xffff0000, v37
	v_pk_mul_f32 v[18:19], v[4:5], v[18:19]
	v_pk_mul_f32 v[16:17], v[12:13], v[16:17]
	v_pk_fma_f32 v[18:19], v[6:7], v[38:39], v[18:19]
	v_pk_fma_f32 v[16:17], v[14:15], v[36:37], v[16:17]
	v_cvt_pk_bf16_f32 v36, v18, v19
	v_cvt_pk_bf16_f32 v37, v16, v17
	v_lshl_add_u64 v[38:39], v[10:11], 0, s[34:35]
	global_store_dwordx2 v[38:39], v[36:37], off nt
	v_lshlrev_b32_e32 v36, 16, v34
	v_and_b32_e32 v37, 0xffff0000, v34
	v_lshlrev_b32_e32 v34, 16, v35
	v_and_b32_e32 v35, 0xffff0000, v35
	v_pk_mul_f32 v[18:19], v[4:5], v[18:19]
	v_pk_mul_f32 v[16:17], v[12:13], v[16:17]
	v_pk_fma_f32 v[18:19], v[6:7], v[36:37], v[18:19]
	v_pk_fma_f32 v[16:17], v[14:15], v[34:35], v[16:17]
	v_cvt_pk_bf16_f32 v34, v18, v19
	v_cvt_pk_bf16_f32 v35, v16, v17
	v_lshl_add_u64 v[36:37], v[10:11], 0, s[30:31]
	global_store_dwordx2 v[36:37], v[34:35], off nt
	v_lshlrev_b32_e32 v34, 16, v32
	v_and_b32_e32 v35, 0xffff0000, v32
	v_lshlrev_b32_e32 v32, 16, v33
	v_and_b32_e32 v33, 0xffff0000, v33
	v_pk_mul_f32 v[18:19], v[4:5], v[18:19]
	v_pk_mul_f32 v[16:17], v[12:13], v[16:17]
	v_pk_fma_f32 v[18:19], v[6:7], v[34:35], v[18:19]
	v_pk_fma_f32 v[16:17], v[14:15], v[32:33], v[16:17]
	v_cvt_pk_bf16_f32 v32, v18, v19
	v_cvt_pk_bf16_f32 v33, v16, v17
	v_lshl_add_u64 v[34:35], v[10:11], 0, s[28:29]
	global_store_dwordx2 v[34:35], v[32:33], off nt
	v_lshlrev_b32_e32 v32, 16, v30
	v_and_b32_e32 v33, 0xffff0000, v30
	v_lshlrev_b32_e32 v30, 16, v31
	v_and_b32_e32 v31, 0xffff0000, v31
	v_pk_mul_f32 v[18:19], v[4:5], v[18:19]
	v_pk_mul_f32 v[16:17], v[12:13], v[16:17]
	v_pk_fma_f32 v[18:19], v[6:7], v[32:33], v[18:19]
	v_pk_fma_f32 v[16:17], v[14:15], v[30:31], v[16:17]
	v_cvt_pk_bf16_f32 v30, v18, v19
	v_cvt_pk_bf16_f32 v31, v16, v17
	v_lshl_add_u64 v[32:33], v[10:11], 0, s[26:27]
	global_store_dwordx2 v[32:33], v[30:31], off nt
	s_waitcnt vmcnt(31)
	v_lshlrev_b32_e32 v30, 16, v28
	v_and_b32_e32 v31, 0xffff0000, v28
	v_lshlrev_b32_e32 v28, 16, v29
	v_and_b32_e32 v29, 0xffff0000, v29
	v_pk_mul_f32 v[18:19], v[4:5], v[18:19]
	v_pk_mul_f32 v[16:17], v[12:13], v[16:17]
	v_pk_fma_f32 v[18:19], v[6:7], v[30:31], v[18:19]
	v_pk_fma_f32 v[16:17], v[14:15], v[28:29], v[16:17]
	v_cvt_pk_bf16_f32 v28, v18, v19
	v_cvt_pk_bf16_f32 v29, v16, v17
	v_lshl_add_u64 v[30:31], v[10:11], 0, s[24:25]
	global_store_dwordx2 v[30:31], v[28:29], off nt
	s_waitcnt vmcnt(30)
	v_lshlrev_b32_e32 v28, 16, v26
	v_and_b32_e32 v29, 0xffff0000, v26
	v_lshlrev_b32_e32 v26, 16, v27
	v_and_b32_e32 v27, 0xffff0000, v27
	v_pk_mul_f32 v[18:19], v[4:5], v[18:19]
	v_pk_mul_f32 v[16:17], v[12:13], v[16:17]
	v_pk_fma_f32 v[18:19], v[6:7], v[28:29], v[18:19]
	v_pk_fma_f32 v[16:17], v[14:15], v[26:27], v[16:17]
	v_cvt_pk_bf16_f32 v26, v18, v19
	v_cvt_pk_bf16_f32 v27, v16, v17
	v_lshl_add_u64 v[28:29], v[10:11], 0, s[22:23]
	global_store_dwordx2 v[28:29], v[26:27], off nt
	s_waitcnt vmcnt(29)
	v_lshlrev_b32_e32 v26, 16, v24
	v_and_b32_e32 v27, 0xffff0000, v24
	v_lshlrev_b32_e32 v24, 16, v25
	v_and_b32_e32 v25, 0xffff0000, v25
	v_pk_mul_f32 v[18:19], v[4:5], v[18:19]
	v_pk_mul_f32 v[16:17], v[12:13], v[16:17]
	v_pk_fma_f32 v[18:19], v[6:7], v[26:27], v[18:19]
	v_pk_fma_f32 v[16:17], v[14:15], v[24:25], v[16:17]
	v_cvt_pk_bf16_f32 v24, v18, v19
	v_cvt_pk_bf16_f32 v25, v16, v17
	v_lshl_add_u64 v[26:27], v[10:11], 0, s[20:21]
	global_store_dwordx2 v[26:27], v[24:25], off nt
	s_waitcnt vmcnt(28)
	v_lshlrev_b32_e32 v24, 16, v22
	v_and_b32_e32 v25, 0xffff0000, v22
	v_lshlrev_b32_e32 v22, 16, v23
	v_and_b32_e32 v23, 0xffff0000, v23
	v_pk_mul_f32 v[18:19], v[4:5], v[18:19]
	v_pk_mul_f32 v[16:17], v[12:13], v[16:17]
	v_pk_fma_f32 v[18:19], v[6:7], v[24:25], v[18:19]
	v_pk_fma_f32 v[16:17], v[14:15], v[22:23], v[16:17]
	v_cvt_pk_bf16_f32 v22, v18, v19
	v_cvt_pk_bf16_f32 v23, v16, v17
	v_lshl_add_u64 v[24:25], v[10:11], 0, s[18:19]
	global_store_dwordx2 v[24:25], v[22:23], off nt
	s_waitcnt vmcnt(27)
	v_lshlrev_b32_e32 v22, 16, v20
	v_and_b32_e32 v23, 0xffff0000, v20
	v_lshlrev_b32_e32 v20, 16, v21
	v_and_b32_e32 v21, 0xffff0000, v21
	v_pk_mul_f32 v[18:19], v[4:5], v[18:19]
	v_pk_mul_f32 v[16:17], v[12:13], v[16:17]
	v_pk_fma_f32 v[18:19], v[6:7], v[22:23], v[18:19]
	v_pk_fma_f32 v[16:17], v[14:15], v[20:21], v[16:17]
	s_mov_b32 s16, 0x800000
	s_mov_b64 s[18:19], 0
	s_cbranch_vccz .LBB0_308
	v_or_b32_e32 v4, v3, v90
	v_lshlrev_b32_e32 v0, 2, v0
	v_ashrrev_i32_e32 v5, 31, v4
	v_lshl_add_u64 v[6:7], s[10:11], 0, v[0:1]
	v_lshlrev_b64 v[8:9], 10, v[4:5]
	v_lshl_add_u64 v[8:9], v[6:7], 0, v[8:9]
	global_store_dword v[8:9], v18, off
	v_or_b32_e32 v8, 1, v4
	v_ashrrev_i32_e32 v9, 31, v8
	v_lshlrev_b64 v[8:9], 10, v[8:9]
	v_lshl_add_u64 v[8:9], v[6:7], 0, v[8:9]
	global_store_dword v[8:9], v19, off
	v_or_b32_e32 v8, 2, v4
	v_or_b32_e32 v4, 3, v4
	v_ashrrev_i32_e32 v9, 31, v8
	v_ashrrev_i32_e32 v5, 31, v4
	v_add_u32_e32 v84, s33, v84
	s_mov_b32 s0, 0xffff
	v_lshlrev_b64 v[8:9], 10, v[8:9]
	v_lshlrev_b64 v[4:5], 10, v[4:5]
	v_cmp_lt_i32_e32 vcc, s0, v84
	v_lshl_add_u64 v[8:9], v[6:7], 0, v[8:9]
	v_lshl_add_u64 v[4:5], v[6:7], 0, v[4:5]
	s_or_b64 s[14:15], vcc, s[14:15]
	global_store_dword v[8:9], v16, off
	global_store_dword v[4:5], v17, off
	s_andn2_b64 exec, exec, s[14:15]
	s_cbranch_execnz .LBB0_307
